# P1 idle-time pool copies throttled: s_sleep 96 per pool group in pool_idle (less HBM interference on workgroups still in their last GEMM unit)
# speedup vs baseline: 1.0112x; 1.0112x over previous
.LBB0_370:
	s_sleep 96
	s_waitcnt vmcnt(0)
	s_barrier
	s_and_saveexec_b64 s[10:11], s[48:49]
	s_cbranch_execz .LBB0_380
	s_xor_b64 s[16:17], s[34:35], -1
	s_andn2_b64 vcc, exec, s[16:17]
	s_cbranch_vccnz .LBB0_375
	s_mov_b64 s[36:37], exec
	v_mbcnt_lo_u32_b32 v8, s36, 0
	v_mbcnt_hi_u32_b32 v8, s37, v8
	v_cmp_eq_u32_e32 vcc, 0, v8
	s_and_saveexec_b64 s[34:35], vcc
	s_cbranch_execz .LBB0_374
	s_load_dwordx4 s[16:19], s[52:53], 0x80
	s_bcnt1_i32_b64 s9, s[36:37]
	v_mov_b32_e32 v8, s9
	s_waitcnt lgkmcnt(0)
	global_atomic_add v1, v8, s[16:17] offset:520
